# relax_epires2 + P1 gate tiles (pn>=10, read only in P3) store with nt via a private copy of the EpiLNP1 epilogue (keeps q/k/VT resident for P2)
# speedup vs baseline: 1.0006x; 1.0006x over previous
;     __device__ __forceinline__ void operator()(const f32x4 (&acc)[2][2][4][2], const Unit& u, int wr, int wc, int fr, int fq) const {
;         const int row0 = u.pm * BM + wr * 64 + fr; const int lc = wc * 32 + 8 * fq; const int pn = u.pn; const bool pair = (pn >= 4) && (pn < 8);
;         int src0, src1, dst0;
;         if (pn < 4) { src0 = 256 * pn; src1 = src0 + 128; dst0 = src0; }
;         else if (pn < 8) { src0 = 1536 + 128 * (pn - 4); src1 = 2560 + 128 * (pn - 4); dst0 = 1024 + 128 * (pn - 4); }
;         else if (pn < 10) { src0 = 2048 + 256 * (pn - 8); src1 = src0 + 128; dst0 = 1536 + 256 * (pn - 8); }
;         else { src0 = 256 * pn + 512; src1 = src0 + 128; dst0 = 256 * pn; }
.LBB0_363:
.LBB0_364:
	s_cmp_gt_i32 s38, 9
	s_cbranch_scc1 .Lg_364
	s_cmp_gt_i32 s38, 3
	s_mov_b64 s[74:75], -1
	s_cbranch_scc0 .LBB0_374
	s_cmp_gt_u32 s38, 7
	s_cbranch_scc0 .LBB0_371
	s_lshl_b32 s34, s38, 8
	s_cmp_gt_u32 s38, 9
	s_cbranch_scc0 .LBB0_368
	s_add_i32 s70, s34, 0x200
	s_add_i32 s60, s34, 0x280
	s_mov_b64 s[74:75], 0

; #define PG8_BAR __builtin_amdgcn_s_barrier()
; template <class Epi, class Sched, bool ALIGN_EPI = false, bool SP2 = false>
; __device__ __forceinline__ void gemm_phase(PG8_LAS unsigned char* lds, const Gemm g, const Sched& S, const Epi& E) {
;     ...
;         if (!has_next) break;
;         if (!keep_acc_)
; #pragma unroll
;         for (int a = 0; a < 2; ++a)
; #pragma unroll
;             for (int b = 0; b < 2; ++b)
; #pragma unroll
;                 for (int m = 0; m < 4; ++m)
; #pragma unroll
;                     for (int n = 0; n < 2; ++n) acc[a][b][m][n] = (f32x4){0.f, 0.f, 0.f, 0.f};
;         cur = nxt; cA = nA; cB = nB; ++ui;
;         if constexpr (ALIGN_EPI) { if (wr == 1) PG8_BAR; }
;     __device__ __forceinline__ void operator()(const f32x4 (&acc)[2][2][4][2], const Unit& u, int wr, int wc, int fr, int fq) const {
;         const int row0 = u.pm * BM + wr * 64 + fr; const int lc = wc * 32 + 8 * fq; const int pn = u.pn; const bool pair = (pn >= 4) && (pn < 8);
;         int src0, src1, dst0;
;         if (pn < 4) { src0 = 256 * pn; src1 = src0 + 128; dst0 = src0; }
;         else if (pn < 8) { src0 = 1536 + 128 * (pn - 4); src1 = 2560 + 128 * (pn - 4); dst0 = 1024 + 128 * (pn - 4); }
;         else if (pn < 10) { src0 = 2048 + 256 * (pn - 8); src1 = src0 + 128; dst0 = 1536 + 256 * (pn - 8); }
;         else { src0 = 256 * pn + 512; src1 = src0 + 128; dst0 = 256 * pn; }
.LBB0_408:
	s_andn2_b64 vcc, exec, s[52:53]
	s_mov_b64 s[34:35], -1
	s_cbranch_vccnz .LBB0_351
	s_andn2_b64 vcc, exec, s[40:41]
	s_cbranch_vccnz .LBB0_350
	s_barrier
	s_branch .LBB0_350
.Lg_364:
	s_cmp_gt_i32 s38, 3
	s_mov_b64 s[74:75], -1
	s_cbranch_scc0 .Lg_374
	s_cmp_gt_u32 s38, 7
	s_cbranch_scc0 .Lg_371
	s_lshl_b32 s34, s38, 8
	s_cmp_gt_u32 s38, 9
	s_cbranch_scc0 .Lg_368
	s_add_i32 s70, s34, 0x200
	s_add_i32 s60, s34, 0x280
	s_mov_b64 s[74:75], 0

; __device__ __forceinline__ unsigned cvt_pk_bf16(float lo, float hi) { unsigned r; asm volatile("v_cvt_pk_bf16_f32 %0, %1, %2" : "=v"(r) : "v"(lo), "v"(hi)); return r; }
; __device__ __forceinline__ void stats_mr(const f32x2 s, float& mu, float& r) { mu = s.x * (1.0f / 1024.0f); const float var = s.y * (1.0f / 1024.0f) - mu * mu; r = __builtin_amdgcn_rsqf(var + 1e-5f); }
;     __device__ __forceinline__ void operator()(const f32x4 (&acc)[2][2][4][2], const Unit& u, int wr, int wc, int fr, int fq) const {
;     ...
;         f32x2 sv[2][4];
; #pragma unroll
;         for (int ai = 0; ai < 2; ++ai)
; #pragma unroll
;             for (int m = 0; m < 4; ++m) sv[ai][m] = *(const f32x2*)(stats + 2 * (size_t)(row0 + ai * HALF + m * 16));
;         f32x4 cv[2][2], bv[2][2];
; #pragma unroll
;         for (int n = 0; n < 2; ++n) { cv[0][n] = *(const f32x4*)(cs + src0 + lc + 4 * n); bv[0][n] = *(const f32x4*)(bc + src0 + lc + 4 * n);
;             cv[1][n] = *(const f32x4*)(cs + src1 + lc + 4 * n); bv[1][n] = *(const f32x4*)(bc + src1 + lc + 4 * n); }
; #pragma unroll
;         for (int ai = 0; ai < 2; ++ai)
; #pragma unroll
;             for (int m = 0; m < 4; ++m) { const int row = row0 + ai * HALF + m * 16; bf16_t* rowp = O + (size_t)row * ldc + dst0 + lc;
;                 float mu, r; stats_mr(sv[ai][m], mu, r);
;                 const f32x4 a0 = (acc[ai][0][m][0] - cv[0][0] * mu) * r + bv[0][0], a1 = (acc[ai][0][m][1] - cv[0][1] * mu) * r + bv[0][1];
;                 const f32x4 b0 = (acc[ai][1][m][0] - cv[1][0] * mu) * r + bv[1][0], b1 = (acc[ai][1][m][1] - cv[1][1] * mu) * r + bv[1][1];
;                 if (pair) { const f32x4 p0 = a0 * b0, p1 = a1 * b1;
;                     u32x4 w; w.x = cvt_pk_bf16(p0[0], p0[1]); w.y = cvt_pk_bf16(p0[2], p0[3]); w.z = cvt_pk_bf16(p1[0], p1[1]); w.w = cvt_pk_bf16(p1[2], p1[3]);
;                     *(u32x4*)(rowp) = w; }
;                 else { u32x4 w; w.x = cvt_pk_bf16(a0[0], a0[1]); w.y = cvt_pk_bf16(a0[2], a0[3]); w.z = cvt_pk_bf16(a1[0], a1[1]); w.w = cvt_pk_bf16(a1[2], a1[3]);
;                     *(u32x4*)(rowp) = w;
;                     u32x4 x; x.x = cvt_pk_bf16(b0[0], b0[1]); x.y = cvt_pk_bf16(b0[2], b0[3]); x.z = cvt_pk_bf16(b1[0], b1[1]); x.w = cvt_pk_bf16(b1[2], b1[3]);
;                     *(u32x4*)(rowp + HALF) = x; } }
.Lg_376:
	v_lshl_add_u64 v[130:131], v[196:197], 3, s[18:19]
	v_ashrrev_i32_e32 v191, 31, v190
	global_load_dwordx2 v[220:221], v[130:131], off
	v_lshl_add_u64 v[130:131], v[190:191], 3, s[18:19]
	v_ashrrev_i32_e32 v189, 31, v188
	global_load_dwordx2 v[214:215], v[130:131], off
	v_lshl_add_u64 v[130:131], v[188:189], 3, s[18:19]
	v_ashrrev_i32_e32 v187, 31, v186
	v_add_u32_e32 v208, 0x80, v196
	global_load_dwordx2 v[212:213], v[130:131], off
	v_lshl_add_u64 v[130:131], v[186:187], 3, s[18:19]
	v_ashrrev_i32_e32 v209, 31, v208
	v_add_u32_e32 v204, 0x90, v196
	s_and_b32 s35, s38, -4
	global_load_dwordx2 v[210:211], v[130:131], off
	v_lshl_add_u64 v[130:131], v[208:209], 3, s[18:19]
	v_ashrrev_i32_e32 v205, 31, v204
	v_add_u32_e32 v200, 0xa0, v196
	s_cmp_lg_u32 s35, 4
	global_load_dwordx2 v[206:207], v[130:131], off
	v_lshl_add_u64 v[130:131], v[204:205], 3, s[18:19]
	v_ashrrev_i32_e32 v201, 31, v200
	v_add_u32_e32 v194, 0xb0, v196
	s_cselect_b64 s[74:75], -1, 0
	global_load_dwordx2 v[202:203], v[130:131], off
	v_lshl_add_u64 v[130:131], v[200:201], 3, s[18:19]
	v_ashrrev_i32_e32 v195, 31, v194
	s_ashr_i32 s71, s70, 31
	global_load_dwordx2 v[198:199], v[130:131], off
	v_lshl_add_u64 v[130:131], v[194:195], 3, s[18:19]
	s_lshl_b64 s[38:39], s[70:71], 2
	s_ashr_i32 s61, s60, 31
	global_load_dwordx2 v[192:193], v[130:131], off
	v_lshl_add_u64 v[130:131], v[172:173], 0, s[38:39]
	v_lshl_add_u64 v[132:133], v[174:175], 0, s[38:39]
	s_lshl_b64 s[38:39], s[60:61], 2
	v_lshl_add_u64 v[142:143], v[172:173], 0, s[38:39]
	v_lshl_add_u64 v[158:159], v[174:175], 0, s[38:39]
	global_load_dwordx4 v[134:137], v[130:131], off offset:16
	global_load_dwordx4 v[154:157], v[130:131], off
	global_load_dwordx4 v[138:141], v[132:133], off offset:16
	global_load_dwordx4 v[150:153], v[132:133], off
	s_nop 0
	global_load_dwordx4 v[130:133], v[142:143], off offset:16
	global_load_dwordx4 v[146:149], v[142:143], off
	s_nop 0
	global_load_dwordx4 v[142:145], v[158:159], off offset:16
	s_nop 0
	global_load_dwordx4 v[158:161], v[158:159], off
	v_mov_b64_e32 v[216:217], s[66:67]
	s_ashr_i32 s35, s34, 31
	v_mad_i64_i32 v[196:197], s[38:39], v196, s55, v[216:217]
	v_lshl_add_u64 v[216:217], s[34:35], 1, v[196:197]
	v_lshlrev_b32_e32 v196, 1, v170
	v_mov_b32_e32 v197, v0
	v_lshl_add_u64 v[216:217], v[216:217], 0, v[196:197]
	s_mov_b64 s[38:39], -1
	s_and_b64 vcc, exec, s[74:75]
	s_waitcnt vmcnt(0)
	v_pk_mul_f32 v[220:221], v[220:221], s[54:55] op_sel_hi:[1,0]
	s_nop 0
	v_fma_f32 v187, -v220, v220, v221
	v_add_f32_e32 v187, 0x3727c5ac, v187
	v_rsq_f32_e32 v234, v187
	v_pk_fma_f32 v[124:125], v[220:221], v[136:137], v[124:125] op_sel_hi:[0,1,1] neg_lo:[1,0,0] neg_hi:[1,0,0]
	v_pk_fma_f32 v[128:129], v[220:221], v[156:157], v[128:129] op_sel_hi:[0,1,1] neg_lo:[1,0,0] neg_hi:[1,0,0]
	v_pk_fma_f32 v[236:237], v[220:221], v[154:155], v[126:127] op_sel_hi:[0,1,1] neg_lo:[1,0,0] neg_hi:[1,0,0]
	v_pk_fma_f32 v[126:127], v[234:235], v[128:129], v[152:153] op_sel_hi:[0,1,1]
	v_pk_fma_f32 v[128:129], v[234:235], v[236:237], v[150:151] op_sel_hi:[0,1,1]
	v_pk_fma_f32 v[236:237], v[220:221], v[134:135], v[122:123] op_sel_hi:[0,1,1] neg_lo:[1,0,0] neg_hi:[1,0,0]
	v_pk_fma_f32 v[122:123], v[234:235], v[124:125], v[140:141] op_sel_hi:[0,1,1]
	v_pk_fma_f32 v[124:125], v[234:235], v[236:237], v[138:139] op_sel_hi:[0,1,1]
	v_pk_fma_f32 v[120:121], v[220:221], v[148:149], v[120:121] op_sel_hi:[0,1,1] neg_lo:[1,0,0] neg_hi:[1,0,0]
	v_pk_fma_f32 v[236:237], v[220:221], v[146:147], v[118:119] op_sel_hi:[0,1,1] neg_lo:[1,0,0] neg_hi:[1,0,0]
	v_pk_fma_f32 v[116:117], v[220:221], v[132:133], v[116:117] op_sel_hi:[0,1,1] neg_lo:[1,0,0] neg_hi:[1,0,0]
	v_pk_fma_f32 v[220:221], v[220:221], v[130:131], v[114:115] op_sel_hi:[0,1,1] neg_lo:[1,0,0] neg_hi:[1,0,0]
	v_pk_fma_f32 v[118:119], v[234:235], v[120:121], v[160:161] op_sel_hi:[0,1,1]
	v_pk_fma_f32 v[120:121], v[234:235], v[236:237], v[158:159] op_sel_hi:[0,1,1]
	v_pk_fma_f32 v[114:115], v[234:235], v[116:117], v[144:145] op_sel_hi:[0,1,1]
	v_pk_fma_f32 v[116:117], v[234:235], v[220:221], v[142:143] op_sel_hi:[0,1,1]
	s_cbranch_vccz .Lg_378
	v_cvt_pk_bf16_f32 v234, v128, v129
	v_cvt_pk_bf16_f32 v235, v126, v127
	v_cvt_pk_bf16_f32 v236, v124, v125
	v_cvt_pk_bf16_f32 v237, v122, v123
	global_store_dwordx4 v[216:217], v[234:237], off nt
	s_mov_b64 s[38:39], 0
	s_nop 0
	v_cvt_pk_bf16_f32 v234, v120, v121
	v_cvt_pk_bf16_f32 v235, v118, v119
	v_cvt_pk_bf16_f32 v236, v116, v117
	v_cvt_pk_bf16_f32 v237, v114, v115
	global_store_dwordx4 v[216:217], v[234:237], off offset:256 nt
.Lg_378:
	s_andn2_b64 vcc, exec, s[38:39]
	s_cbranch_vccnz .Lg_380
	v_pk_mul_f32 v[116:117], v[124:125], v[116:117]
	v_pk_mul_f32 v[118:119], v[126:127], v[118:119]
	v_pk_mul_f32 v[120:121], v[128:129], v[120:121]
	v_pk_mul_f32 v[122:123], v[122:123], v[114:115]
	v_cvt_pk_bf16_f32 v114, v120, v121
	v_cvt_pk_bf16_f32 v115, v118, v119
	v_cvt_pk_bf16_f32 v116, v116, v117
	s_nop 0
	v_cvt_pk_bf16_f32 v117, v122, v123
	global_store_dwordx4 v[216:217], v[114:117], off nt
; __device__ __forceinline__ unsigned cvt_pk_bf16(float lo, float hi) { unsigned r; asm volatile("v_cvt_pk_bf16_f32 %0, %1, %2" : "=v"(r) : "v"(lo), "v"(hi)); return r; }
; __device__ __forceinline__ void stats_mr(const f32x2 s, float& mu, float& r) { mu = s.x * (1.0f / 1024.0f); const float var = s.y * (1.0f / 1024.0f) - mu * mu; r = __builtin_amdgcn_rsqf(var + 1e-5f); }
;     __device__ __forceinline__ void operator()(const f32x4 (&acc)[2][2][4][2], const Unit& u, int wr, int wc, int fr, int fq) const {
;     ...
;             for (int m = 0; m < 4; ++m) { const int row = row0 + ai * HALF + m * 16; bf16_t* rowp = O + (size_t)row * ldc + dst0 + lc;
;                 float mu, r; stats_mr(sv[ai][m], mu, r);
;                 const f32x4 a0 = (acc[ai][0][m][0] - cv[0][0] * mu) * r + bv[0][0], a1 = (acc[ai][0][m][1] - cv[0][1] * mu) * r + bv[0][1];
;                 const f32x4 b0 = (acc[ai][1][m][0] - cv[1][0] * mu) * r + bv[1][0], b1 = (acc[ai][1][m][1] - cv[1][1] * mu) * r + bv[1][1];
;                 if (pair) { const f32x4 p0 = a0 * b0, p1 = a1 * b1;
;                     u32x4 w; w.x = cvt_pk_bf16(p0[0], p0[1]); w.y = cvt_pk_bf16(p0[2], p0[3]); w.z = cvt_pk_bf16(p1[0], p1[1]); w.w = cvt_pk_bf16(p1[2], p1[3]);
;                     *(u32x4*)(rowp) = w; }
;                 else { u32x4 w; w.x = cvt_pk_bf16(a0[0], a0[1]); w.y = cvt_pk_bf16(a0[2], a0[3]); w.z = cvt_pk_bf16(a1[0], a1[1]); w.w = cvt_pk_bf16(a1[2], a1[3]);
;                     *(u32x4*)(rowp) = w;
;                     u32x4 x; x.x = cvt_pk_bf16(b0[0], b0[1]); x.y = cvt_pk_bf16(b0[2], b0[3]); x.z = cvt_pk_bf16(b1[0], b1[1]); x.w = cvt_pk_bf16(b1[2], b1[3]);
;                     *(u32x4*)(rowp + HALF) = x; } }
.Lg_380:
	s_nop 1
	v_pk_mul_f32 v[116:117], v[214:215], s[54:55] op_sel_hi:[1,0]
	v_mov_b64_e32 v[114:115], s[66:67]
	v_fma_f32 v118, -v116, v116, v117
	v_add_f32_e32 v118, 0x3727c5ac, v118
	v_rsq_f32_e32 v118, v118
	v_pk_fma_f32 v[112:113], v[116:117], v[156:157], v[112:113] op_sel_hi:[0,1,1] neg_lo:[1,0,0] neg_hi:[1,0,0]
	v_pk_fma_f32 v[120:121], v[116:117], v[154:155], v[110:111] op_sel_hi:[0,1,1] neg_lo:[1,0,0] neg_hi:[1,0,0]
	v_pk_fma_f32 v[108:109], v[116:117], v[136:137], v[108:109] op_sel_hi:[0,1,1] neg_lo:[1,0,0] neg_hi:[1,0,0]
	v_pk_fma_f32 v[110:111], v[118:119], v[112:113], v[152:153] op_sel_hi:[0,1,1]
	v_pk_fma_f32 v[112:113], v[118:119], v[120:121], v[150:151] op_sel_hi:[0,1,1]
	v_pk_fma_f32 v[120:121], v[116:117], v[134:135], v[106:107] op_sel_hi:[0,1,1] neg_lo:[1,0,0] neg_hi:[1,0,0]
	v_mad_i64_i32 v[114:115], s[38:39], v190, s55, v[114:115]
	v_pk_fma_f32 v[106:107], v[118:119], v[108:109], v[140:141] op_sel_hi:[0,1,1]
	v_pk_fma_f32 v[108:109], v[118:119], v[120:121], v[138:139] op_sel_hi:[0,1,1]
	v_pk_fma_f32 v[104:105], v[116:117], v[148:149], v[104:105] op_sel_hi:[0,1,1] neg_lo:[1,0,0] neg_hi:[1,0,0]
	v_pk_fma_f32 v[120:121], v[116:117], v[146:147], v[102:103] op_sel_hi:[0,1,1] neg_lo:[1,0,0] neg_hi:[1,0,0]
	v_pk_fma_f32 v[100:101], v[116:117], v[132:133], v[100:101] op_sel_hi:[0,1,1] neg_lo:[1,0,0] neg_hi:[1,0,0]
	v_pk_fma_f32 v[116:117], v[116:117], v[130:131], v[98:99] op_sel_hi:[0,1,1] neg_lo:[1,0,0] neg_hi:[1,0,0]
	v_lshl_add_u64 v[114:115], s[34:35], 1, v[114:115]
	v_mov_b32_e32 v197, v0
	v_pk_fma_f32 v[98:99], v[118:119], v[100:101], v[144:145] op_sel_hi:[0,1,1]
	v_pk_fma_f32 v[100:101], v[118:119], v[116:117], v[142:143] op_sel_hi:[0,1,1]
	v_cndmask_b32_e64 v116, 0, 1, s[74:75]
	v_lshl_add_u64 v[114:115], v[114:115], 0, v[196:197]
	v_pk_fma_f32 v[102:103], v[118:119], v[104:105], v[160:161] op_sel_hi:[0,1,1]
	v_pk_fma_f32 v[104:105], v[118:119], v[120:121], v[158:159] op_sel_hi:[0,1,1]
	s_mov_b64 s[60:61], -1
	v_cmp_ne_u32_e64 s[38:39], 1, v116
	s_andn2_b64 vcc, exec, s[74:75]
	s_cbranch_vccnz .Lg_382
	v_cvt_pk_bf16_f32 v116, v112, v113
	v_cvt_pk_bf16_f32 v117, v110, v111
	v_cvt_pk_bf16_f32 v118, v108, v109
	v_cvt_pk_bf16_f32 v119, v106, v107
	s_mov_b64 s[60:61], 0
	global_store_dwordx4 v[114:115], v[116:119], off nt
	s_nop 1
	v_cvt_pk_bf16_f32 v116, v104, v105
	v_cvt_pk_bf16_f32 v117, v102, v103
	v_cvt_pk_bf16_f32 v118, v100, v101
	v_cvt_pk_bf16_f32 v119, v98, v99
	global_store_dwordx4 v[114:115], v[116:119], off offset:256 nt
.Lg_382:
	s_andn2_b64 vcc, exec, s[60:61]
	s_cbranch_vccnz .Lg_384
	v_pk_mul_f32 v[100:101], v[108:109], v[100:101]
	v_pk_mul_f32 v[102:103], v[110:111], v[102:103]
	v_pk_mul_f32 v[104:105], v[112:113], v[104:105]
	v_pk_mul_f32 v[106:107], v[106:107], v[98:99]
	v_cvt_pk_bf16_f32 v98, v104, v105
	v_cvt_pk_bf16_f32 v99, v102, v103
	v_cvt_pk_bf16_f32 v100, v100, v101
	s_nop 0
	v_cvt_pk_bf16_f32 v101, v106, v107
	global_store_dwordx4 v[114:115], v[98:101], off nt
.Lg_384:
	s_nop 1
	v_pk_mul_f32 v[100:101], v[212:213], s[54:55] op_sel_hi:[1,0]
	v_mov_b64_e32 v[98:99], s[66:67]
	v_fma_f32 v102, -v100, v100, v101
	v_add_f32_e32 v102, 0x3727c5ac, v102
	v_rsq_f32_e32 v102, v102
	v_pk_fma_f32 v[96:97], v[100:101], v[156:157], v[96:97] op_sel_hi:[0,1,1] neg_lo:[1,0,0] neg_hi:[1,0,0]
	v_pk_fma_f32 v[104:105], v[100:101], v[154:155], v[94:95] op_sel_hi:[0,1,1] neg_lo:[1,0,0] neg_hi:[1,0,0]
	v_mad_i64_i32 v[98:99], s[60:61], v188, s55, v[98:99]
	v_pk_fma_f32 v[94:95], v[102:103], v[96:97], v[152:153] op_sel_hi:[0,1,1]
	v_pk_fma_f32 v[96:97], v[102:103], v[104:105], v[150:151] op_sel_hi:[0,1,1]
	v_pk_fma_f32 v[92:93], v[100:101], v[136:137], v[92:93] op_sel_hi:[0,1,1] neg_lo:[1,0,0] neg_hi:[1,0,0]
	v_pk_fma_f32 v[104:105], v[100:101], v[134:135], v[90:91] op_sel_hi:[0,1,1] neg_lo:[1,0,0] neg_hi:[1,0,0]
	v_lshl_add_u64 v[98:99], s[34:35], 1, v[98:99]
	v_mov_b32_e32 v197, v0
	v_pk_fma_f32 v[90:91], v[102:103], v[92:93], v[140:141] op_sel_hi:[0,1,1]
	v_pk_fma_f32 v[92:93], v[102:103], v[104:105], v[138:139] op_sel_hi:[0,1,1]
	v_pk_fma_f32 v[88:89], v[100:101], v[148:149], v[88:89] op_sel_hi:[0,1,1] neg_lo:[1,0,0] neg_hi:[1,0,0]
	v_pk_fma_f32 v[104:105], v[100:101], v[146:147], v[86:87] op_sel_hi:[0,1,1] neg_lo:[1,0,0] neg_hi:[1,0,0]
	v_pk_fma_f32 v[84:85], v[100:101], v[132:133], v[84:85] op_sel_hi:[0,1,1] neg_lo:[1,0,0] neg_hi:[1,0,0]
	v_pk_fma_f32 v[100:101], v[100:101], v[130:131], v[82:83] op_sel_hi:[0,1,1] neg_lo:[1,0,0] neg_hi:[1,0,0]
	v_lshl_add_u64 v[98:99], v[98:99], 0, v[196:197]
	v_pk_fma_f32 v[86:87], v[102:103], v[88:89], v[160:161] op_sel_hi:[0,1,1]
	v_pk_fma_f32 v[88:89], v[102:103], v[104:105], v[158:159] op_sel_hi:[0,1,1]
	v_pk_fma_f32 v[82:83], v[102:103], v[84:85], v[144:145] op_sel_hi:[0,1,1]
	v_pk_fma_f32 v[84:85], v[102:103], v[100:101], v[142:143] op_sel_hi:[0,1,1]
	s_mov_b64 s[60:61], -1
	s_and_b64 vcc, exec, s[38:39]
	s_cbranch_vccnz .Lg_386
	v_cvt_pk_bf16_f32 v100, v96, v97
	v_cvt_pk_bf16_f32 v101, v94, v95
	v_cvt_pk_bf16_f32 v102, v92, v93
	v_cvt_pk_bf16_f32 v103, v90, v91
	s_mov_b64 s[60:61], 0
	global_store_dwordx4 v[98:99], v[100:103], off nt
	s_nop 1
	v_cvt_pk_bf16_f32 v100, v88, v89
	v_cvt_pk_bf16_f32 v101, v86, v87
	v_cvt_pk_bf16_f32 v102, v84, v85
	v_cvt_pk_bf16_f32 v103, v82, v83
	global_store_dwordx4 v[98:99], v[100:103], off offset:256 nt
.Lg_386:
	s_andn2_b64 vcc, exec, s[60:61]
	s_cbranch_vccnz .Lg_388
	v_pk_mul_f32 v[84:85], v[92:93], v[84:85]
	v_pk_mul_f32 v[86:87], v[94:95], v[86:87]
	v_pk_mul_f32 v[88:89], v[96:97], v[88:89]
	v_pk_mul_f32 v[90:91], v[90:91], v[82:83]
	v_cvt_pk_bf16_f32 v82, v88, v89
	v_cvt_pk_bf16_f32 v83, v86, v87
	v_cvt_pk_bf16_f32 v84, v84, v85
	s_nop 0
	v_cvt_pk_bf16_f32 v85, v90, v91
	global_store_dwordx4 v[98:99], v[82:85], off nt
; __device__ __forceinline__ unsigned cvt_pk_bf16(float lo, float hi) { unsigned r; asm volatile("v_cvt_pk_bf16_f32 %0, %1, %2" : "=v"(r) : "v"(lo), "v"(hi)); return r; }
; __device__ __forceinline__ void stats_mr(const f32x2 s, float& mu, float& r) { mu = s.x * (1.0f / 1024.0f); const float var = s.y * (1.0f / 1024.0f) - mu * mu; r = __builtin_amdgcn_rsqf(var + 1e-5f); }
;     __device__ __forceinline__ void operator()(const f32x4 (&acc)[2][2][4][2], const Unit& u, int wr, int wc, int fr, int fq) const {
;     ...
;             for (int m = 0; m < 4; ++m) { const int row = row0 + ai * HALF + m * 16; bf16_t* rowp = O + (size_t)row * ldc + dst0 + lc;
;                 float mu, r; stats_mr(sv[ai][m], mu, r);
;                 const f32x4 a0 = (acc[ai][0][m][0] - cv[0][0] * mu) * r + bv[0][0], a1 = (acc[ai][0][m][1] - cv[0][1] * mu) * r + bv[0][1];
;                 const f32x4 b0 = (acc[ai][1][m][0] - cv[1][0] * mu) * r + bv[1][0], b1 = (acc[ai][1][m][1] - cv[1][1] * mu) * r + bv[1][1];
;                 if (pair) { const f32x4 p0 = a0 * b0, p1 = a1 * b1;
;                     u32x4 w; w.x = cvt_pk_bf16(p0[0], p0[1]); w.y = cvt_pk_bf16(p0[2], p0[3]); w.z = cvt_pk_bf16(p1[0], p1[1]); w.w = cvt_pk_bf16(p1[2], p1[3]);
;                     *(u32x4*)(rowp) = w; }
;                 else { u32x4 w; w.x = cvt_pk_bf16(a0[0], a0[1]); w.y = cvt_pk_bf16(a0[2], a0[3]); w.z = cvt_pk_bf16(a1[0], a1[1]); w.w = cvt_pk_bf16(a1[2], a1[3]);
;                     *(u32x4*)(rowp) = w;
;                     u32x4 x; x.x = cvt_pk_bf16(b0[0], b0[1]); x.y = cvt_pk_bf16(b0[2], b0[3]); x.z = cvt_pk_bf16(b1[0], b1[1]); x.w = cvt_pk_bf16(b1[2], b1[3]);
;                     *(u32x4*)(rowp + HALF) = x; } }
.Lg_388:
	s_nop 1
	v_pk_mul_f32 v[84:85], v[210:211], s[54:55] op_sel_hi:[1,0]
	v_mov_b64_e32 v[82:83], s[66:67]
	v_fma_f32 v86, -v84, v84, v85
	v_add_f32_e32 v86, 0x3727c5ac, v86
	v_rsq_f32_e32 v86, v86
	v_pk_fma_f32 v[80:81], v[84:85], v[156:157], v[80:81] op_sel_hi:[0,1,1] neg_lo:[1,0,0] neg_hi:[1,0,0]
	v_pk_fma_f32 v[88:89], v[84:85], v[154:155], v[78:79] op_sel_hi:[0,1,1] neg_lo:[1,0,0] neg_hi:[1,0,0]
	v_mad_i64_i32 v[82:83], s[60:61], v186, s55, v[82:83]
	v_pk_fma_f32 v[78:79], v[80:81], v[86:87], v[152:153] op_sel_hi:[1,0,1]
	v_pk_fma_f32 v[80:81], v[88:89], v[86:87], v[150:151] op_sel_hi:[1,0,1]
	v_pk_fma_f32 v[76:77], v[84:85], v[136:137], v[76:77] op_sel_hi:[0,1,1] neg_lo:[1,0,0] neg_hi:[1,0,0]
	v_pk_fma_f32 v[88:89], v[84:85], v[134:135], v[74:75] op_sel_hi:[0,1,1] neg_lo:[1,0,0] neg_hi:[1,0,0]
	v_lshl_add_u64 v[82:83], s[34:35], 1, v[82:83]
	v_mov_b32_e32 v197, v0
	v_pk_fma_f32 v[74:75], v[86:87], v[76:77], v[140:141] op_sel_hi:[0,1,1]
	v_pk_fma_f32 v[76:77], v[86:87], v[88:89], v[138:139] op_sel_hi:[0,1,1]
	v_pk_fma_f32 v[72:73], v[84:85], v[148:149], v[72:73] op_sel_hi:[0,1,1] neg_lo:[1,0,0] neg_hi:[1,0,0]
	v_pk_fma_f32 v[88:89], v[84:85], v[146:147], v[70:71] op_sel_hi:[0,1,1] neg_lo:[1,0,0] neg_hi:[1,0,0]
	v_pk_fma_f32 v[68:69], v[84:85], v[132:133], v[68:69] op_sel_hi:[0,1,1] neg_lo:[1,0,0] neg_hi:[1,0,0]
	v_pk_fma_f32 v[84:85], v[84:85], v[130:131], v[66:67] op_sel_hi:[0,1,1] neg_lo:[1,0,0] neg_hi:[1,0,0]
	v_lshl_add_u64 v[82:83], v[82:83], 0, v[196:197]
	v_pk_fma_f32 v[70:71], v[86:87], v[72:73], v[160:161] op_sel_hi:[0,1,1]
	v_pk_fma_f32 v[72:73], v[86:87], v[88:89], v[158:159] op_sel_hi:[0,1,1]
	v_pk_fma_f32 v[66:67], v[86:87], v[68:69], v[144:145] op_sel_hi:[0,1,1]
	v_pk_fma_f32 v[68:69], v[86:87], v[84:85], v[142:143] op_sel_hi:[0,1,1]
	s_mov_b64 s[60:61], -1
	s_and_b64 vcc, exec, s[38:39]
	s_cbranch_vccnz .Lg_390
	v_cvt_pk_bf16_f32 v84, v80, v81
	v_cvt_pk_bf16_f32 v85, v78, v79
	v_cvt_pk_bf16_f32 v86, v76, v77
	v_cvt_pk_bf16_f32 v87, v74, v75
	s_mov_b64 s[60:61], 0
	global_store_dwordx4 v[82:83], v[84:87], off nt
	s_nop 1
	v_cvt_pk_bf16_f32 v84, v72, v73
	v_cvt_pk_bf16_f32 v85, v70, v71
	v_cvt_pk_bf16_f32 v86, v68, v69
	v_cvt_pk_bf16_f32 v87, v66, v67
	global_store_dwordx4 v[82:83], v[84:87], off offset:256 nt
.Lg_390:
	s_andn2_b64 vcc, exec, s[60:61]
	s_cbranch_vccnz .Lg_392
	v_pk_mul_f32 v[68:69], v[76:77], v[68:69]
	v_pk_mul_f32 v[70:71], v[78:79], v[70:71]
	v_pk_mul_f32 v[72:73], v[80:81], v[72:73]
	v_pk_mul_f32 v[74:75], v[74:75], v[66:67]
	v_cvt_pk_bf16_f32 v66, v72, v73
	v_cvt_pk_bf16_f32 v67, v70, v71
	v_cvt_pk_bf16_f32 v68, v68, v69
	s_nop 0
	v_cvt_pk_bf16_f32 v69, v74, v75
	global_store_dwordx4 v[82:83], v[66:69], off nt
.Lg_392:
	s_nop 1
	v_pk_mul_f32 v[68:69], v[206:207], s[54:55] op_sel_hi:[1,0]
	v_mov_b64_e32 v[66:67], s[66:67]
	v_fma_f32 v70, -v68, v68, v69
	v_add_f32_e32 v70, 0x3727c5ac, v70
	v_rsq_f32_e32 v70, v70
	v_pk_fma_f32 v[64:65], v[68:69], v[156:157], v[64:65] op_sel_hi:[0,1,1] neg_lo:[1,0,0] neg_hi:[1,0,0]
	v_pk_fma_f32 v[72:73], v[68:69], v[154:155], v[62:63] op_sel_hi:[0,1,1] neg_lo:[1,0,0] neg_hi:[1,0,0]
	v_mad_i64_i32 v[66:67], s[60:61], v208, s55, v[66:67]
	v_pk_fma_f32 v[62:63], v[64:65], v[70:71], v[152:153] op_sel_hi:[1,0,1]
	v_pk_fma_f32 v[64:65], v[72:73], v[70:71], v[150:151] op_sel_hi:[1,0,1]
	v_pk_fma_f32 v[60:61], v[68:69], v[136:137], v[60:61] op_sel_hi:[0,1,1] neg_lo:[1,0,0] neg_hi:[1,0,0]
	v_pk_fma_f32 v[72:73], v[68:69], v[134:135], v[58:59] op_sel_hi:[0,1,1] neg_lo:[1,0,0] neg_hi:[1,0,0]
	v_lshl_add_u64 v[66:67], s[34:35], 1, v[66:67]
	v_mov_b32_e32 v197, v0
	v_pk_fma_f32 v[58:59], v[70:71], v[60:61], v[140:141] op_sel_hi:[0,1,1]
	v_pk_fma_f32 v[60:61], v[70:71], v[72:73], v[138:139] op_sel_hi:[0,1,1]
	v_pk_fma_f32 v[56:57], v[68:69], v[148:149], v[56:57] op_sel_hi:[0,1,1] neg_lo:[1,0,0] neg_hi:[1,0,0]
	v_pk_fma_f32 v[72:73], v[68:69], v[146:147], v[54:55] op_sel_hi:[0,1,1] neg_lo:[1,0,0] neg_hi:[1,0,0]
	v_pk_fma_f32 v[52:53], v[68:69], v[132:133], v[52:53] op_sel_hi:[0,1,1] neg_lo:[1,0,0] neg_hi:[1,0,0]
	v_pk_fma_f32 v[68:69], v[68:69], v[130:131], v[50:51] op_sel_hi:[0,1,1] neg_lo:[1,0,0] neg_hi:[1,0,0]
	v_lshl_add_u64 v[66:67], v[66:67], 0, v[196:197]
	v_pk_fma_f32 v[54:55], v[70:71], v[56:57], v[160:161] op_sel_hi:[0,1,1]
	v_pk_fma_f32 v[56:57], v[70:71], v[72:73], v[158:159] op_sel_hi:[0,1,1]
	v_pk_fma_f32 v[50:51], v[70:71], v[52:53], v[144:145] op_sel_hi:[0,1,1]
	v_pk_fma_f32 v[52:53], v[70:71], v[68:69], v[142:143] op_sel_hi:[0,1,1]
	s_mov_b64 s[60:61], -1
	s_and_b64 vcc, exec, s[38:39]
	s_cbranch_vccnz .Lg_394
	v_cvt_pk_bf16_f32 v68, v64, v65
	v_cvt_pk_bf16_f32 v69, v62, v63
	v_cvt_pk_bf16_f32 v70, v60, v61
	v_cvt_pk_bf16_f32 v71, v58, v59
	s_mov_b64 s[60:61], 0
	global_store_dwordx4 v[66:67], v[68:71], off nt
	s_nop 1
	v_cvt_pk_bf16_f32 v68, v56, v57
	v_cvt_pk_bf16_f32 v69, v54, v55
	v_cvt_pk_bf16_f32 v70, v52, v53
	v_cvt_pk_bf16_f32 v71, v50, v51
	global_store_dwordx4 v[66:67], v[68:71], off offset:256 nt
.Lg_394:
	s_andn2_b64 vcc, exec, s[60:61]
	s_cbranch_vccnz .Lg_396
	v_pk_mul_f32 v[52:53], v[60:61], v[52:53]
	v_pk_mul_f32 v[54:55], v[62:63], v[54:55]
	v_pk_mul_f32 v[56:57], v[64:65], v[56:57]
	v_pk_mul_f32 v[58:59], v[58:59], v[50:51]
	v_cvt_pk_bf16_f32 v50, v56, v57
	v_cvt_pk_bf16_f32 v51, v54, v55
	v_cvt_pk_bf16_f32 v52, v52, v53
	s_nop 0
	v_cvt_pk_bf16_f32 v53, v58, v59
	global_store_dwordx4 v[66:67], v[50:53], off nt
; __device__ __forceinline__ unsigned cvt_pk_bf16(float lo, float hi) { unsigned r; asm volatile("v_cvt_pk_bf16_f32 %0, %1, %2" : "=v"(r) : "v"(lo), "v"(hi)); return r; }
; __device__ __forceinline__ void stats_mr(const f32x2 s, float& mu, float& r) { mu = s.x * (1.0f / 1024.0f); const float var = s.y * (1.0f / 1024.0f) - mu * mu; r = __builtin_amdgcn_rsqf(var + 1e-5f); }
;     __device__ __forceinline__ void operator()(const f32x4 (&acc)[2][2][4][2], const Unit& u, int wr, int wc, int fr, int fq) const {
;     ...
;             for (int m = 0; m < 4; ++m) { const int row = row0 + ai * HALF + m * 16; bf16_t* rowp = O + (size_t)row * ldc + dst0 + lc;
;                 float mu, r; stats_mr(sv[ai][m], mu, r);
;                 const f32x4 a0 = (acc[ai][0][m][0] - cv[0][0] * mu) * r + bv[0][0], a1 = (acc[ai][0][m][1] - cv[0][1] * mu) * r + bv[0][1];
;                 const f32x4 b0 = (acc[ai][1][m][0] - cv[1][0] * mu) * r + bv[1][0], b1 = (acc[ai][1][m][1] - cv[1][1] * mu) * r + bv[1][1];
;                 if (pair) { const f32x4 p0 = a0 * b0, p1 = a1 * b1;
;                     u32x4 w; w.x = cvt_pk_bf16(p0[0], p0[1]); w.y = cvt_pk_bf16(p0[2], p0[3]); w.z = cvt_pk_bf16(p1[0], p1[1]); w.w = cvt_pk_bf16(p1[2], p1[3]);
;                     *(u32x4*)(rowp) = w; }
;                 else { u32x4 w; w.x = cvt_pk_bf16(a0[0], a0[1]); w.y = cvt_pk_bf16(a0[2], a0[3]); w.z = cvt_pk_bf16(a1[0], a1[1]); w.w = cvt_pk_bf16(a1[2], a1[3]);
;                     *(u32x4*)(rowp) = w;
;                     u32x4 x; x.x = cvt_pk_bf16(b0[0], b0[1]); x.y = cvt_pk_bf16(b0[2], b0[3]); x.z = cvt_pk_bf16(b1[0], b1[1]); x.w = cvt_pk_bf16(b1[2], b1[3]);
;                     *(u32x4*)(rowp + HALF) = x; } }
.Lg_396:
	s_nop 1
	v_mov_b64_e32 v[50:51], s[66:67]
	v_mad_i64_i32 v[50:51], s[60:61], v204, s55, v[50:51]
	v_lshl_add_u64 v[50:51], s[34:35], 1, v[50:51]
	v_mov_b32_e32 v197, v0
	v_pk_mul_f32 v[54:55], v[202:203], s[54:55] op_sel_hi:[1,0]
	v_lshl_add_u64 v[52:53], v[50:51], 0, v[196:197]
	v_fma_f32 v50, -v54, v54, v55
	v_add_f32_e32 v50, 0x3727c5ac, v50
	v_rsq_f32_e32 v56, v50
	v_xor_b32_e32 v51, 0x80000000, v157
	v_xor_b32_e32 v50, 0x80000000, v156
	v_pk_fma_f32 v[48:49], v[50:51], v[54:55], v[48:49] op_sel_hi:[1,0,1]
	v_pk_fma_f32 v[58:59], v[154:155], v[54:55], v[46:47] op_sel_hi:[1,0,1] neg_lo:[1,0,0] neg_hi:[1,0,0]
	v_pk_fma_f32 v[46:47], v[48:49], v[56:57], v[152:153] op_sel_hi:[1,0,1]
	v_pk_fma_f32 v[48:49], v[58:59], v[56:57], v[150:151] op_sel_hi:[1,0,1]
	v_pk_fma_f32 v[44:45], v[54:55], v[136:137], v[44:45] op_sel_hi:[0,1,1] neg_lo:[1,0,0] neg_hi:[1,0,0]
	v_pk_fma_f32 v[58:59], v[54:55], v[134:135], v[42:43] op_sel_hi:[0,1,1] neg_lo:[1,0,0] neg_hi:[1,0,0]
	v_pk_fma_f32 v[42:43], v[56:57], v[44:45], v[140:141] op_sel_hi:[0,1,1]
	v_pk_fma_f32 v[44:45], v[56:57], v[58:59], v[138:139] op_sel_hi:[0,1,1]
	v_pk_fma_f32 v[40:41], v[54:55], v[148:149], v[40:41] op_sel_hi:[0,1,1] neg_lo:[1,0,0] neg_hi:[1,0,0]
	v_pk_fma_f32 v[58:59], v[54:55], v[146:147], v[38:39] op_sel_hi:[0,1,1] neg_lo:[1,0,0] neg_hi:[1,0,0]
	v_pk_fma_f32 v[36:37], v[54:55], v[132:133], v[36:37] op_sel_hi:[0,1,1] neg_lo:[1,0,0] neg_hi:[1,0,0]
	v_pk_fma_f32 v[54:55], v[54:55], v[130:131], v[34:35] op_sel_hi:[0,1,1] neg_lo:[1,0,0] neg_hi:[1,0,0]
	v_pk_fma_f32 v[38:39], v[40:41], v[56:57], v[160:161] op_sel_hi:[1,0,1]
	v_pk_fma_f32 v[40:41], v[58:59], v[56:57], v[158:159] op_sel_hi:[1,0,1]
	v_pk_fma_f32 v[34:35], v[56:57], v[36:37], v[144:145] op_sel_hi:[0,1,1]
	v_pk_fma_f32 v[36:37], v[56:57], v[54:55], v[142:143] op_sel_hi:[0,1,1]
	s_and_b64 vcc, exec, s[38:39]
	s_mov_b64 s[60:61], -1
	s_cbranch_vccnz .Lg_398
	v_cvt_pk_bf16_f32 v54, v48, v49
	v_cvt_pk_bf16_f32 v55, v46, v47
	v_cvt_pk_bf16_f32 v56, v44, v45
	v_cvt_pk_bf16_f32 v57, v42, v43
	s_mov_b64 s[60:61], 0
	global_store_dwordx4 v[52:53], v[54:57], off nt
	s_nop 1
	v_cvt_pk_bf16_f32 v54, v40, v41
	v_cvt_pk_bf16_f32 v55, v38, v39
	v_cvt_pk_bf16_f32 v56, v36, v37
	v_cvt_pk_bf16_f32 v57, v34, v35
	global_store_dwordx4 v[52:53], v[54:57], off offset:256 nt
.Lg_398:
	s_andn2_b64 vcc, exec, s[60:61]
	s_cbranch_vccnz .Lg_400
	v_pk_mul_f32 v[36:37], v[44:45], v[36:37]
	v_pk_mul_f32 v[38:39], v[46:47], v[38:39]
	v_pk_mul_f32 v[40:41], v[48:49], v[40:41]
	v_pk_mul_f32 v[42:43], v[42:43], v[34:35]
	v_cvt_pk_bf16_f32 v34, v40, v41
	v_cvt_pk_bf16_f32 v35, v38, v39
	v_cvt_pk_bf16_f32 v36, v36, v37
	s_nop 0
	v_cvt_pk_bf16_f32 v37, v42, v43
	global_store_dwordx4 v[52:53], v[34:37], off nt
.Lg_400:
	s_nop 1
	v_pk_mul_f32 v[36:37], v[198:199], s[54:55] op_sel_hi:[1,0]
	v_mov_b64_e32 v[34:35], s[66:67]
	v_fma_f32 v38, -v36, v36, v37
	v_add_f32_e32 v38, 0x3727c5ac, v38
	v_rsq_f32_e32 v38, v38
	v_pk_fma_f32 v[32:33], v[50:51], v[36:37], v[32:33] op_sel_hi:[1,0,1]
	v_pk_fma_f32 v[40:41], v[154:155], v[36:37], v[30:31] op_sel_hi:[1,0,1] neg_lo:[1,0,0] neg_hi:[1,0,0]
	v_mad_i64_i32 v[34:35], s[60:61], v200, s55, v[34:35]
	v_pk_fma_f32 v[30:31], v[32:33], v[38:39], v[152:153] op_sel_hi:[1,0,1]
	v_pk_fma_f32 v[32:33], v[40:41], v[38:39], v[150:151] op_sel_hi:[1,0,1]
	v_pk_fma_f32 v[28:29], v[36:37], v[136:137], v[28:29] op_sel_hi:[0,1,1] neg_lo:[1,0,0] neg_hi:[1,0,0]
	v_pk_fma_f32 v[40:41], v[36:37], v[134:135], v[26:27] op_sel_hi:[0,1,1] neg_lo:[1,0,0] neg_hi:[1,0,0]
	v_lshl_add_u64 v[34:35], s[34:35], 1, v[34:35]
	v_mov_b32_e32 v197, v0
	v_pk_fma_f32 v[26:27], v[38:39], v[28:29], v[140:141] op_sel_hi:[0,1,1]
	v_pk_fma_f32 v[28:29], v[38:39], v[40:41], v[138:139] op_sel_hi:[0,1,1]
	v_pk_fma_f32 v[24:25], v[36:37], v[148:149], v[24:25] op_sel_hi:[0,1,1] neg_lo:[1,0,0] neg_hi:[1,0,0]
	v_pk_fma_f32 v[40:41], v[36:37], v[146:147], v[22:23] op_sel_hi:[0,1,1] neg_lo:[1,0,0] neg_hi:[1,0,0]
	v_pk_fma_f32 v[20:21], v[36:37], v[132:133], v[20:21] op_sel_hi:[0,1,1] neg_lo:[1,0,0] neg_hi:[1,0,0]
	v_pk_fma_f32 v[36:37], v[36:37], v[130:131], v[18:19] op_sel_hi:[0,1,1] neg_lo:[1,0,0] neg_hi:[1,0,0]
	v_lshl_add_u64 v[34:35], v[34:35], 0, v[196:197]
	v_pk_fma_f32 v[22:23], v[24:25], v[38:39], v[160:161] op_sel_hi:[1,0,1]
	v_pk_fma_f32 v[24:25], v[40:41], v[38:39], v[158:159] op_sel_hi:[1,0,1]
	v_pk_fma_f32 v[18:19], v[38:39], v[20:21], v[144:145] op_sel_hi:[0,1,1]
	v_pk_fma_f32 v[20:21], v[38:39], v[36:37], v[142:143] op_sel_hi:[0,1,1]
	s_mov_b64 s[60:61], -1
	s_and_b64 vcc, exec, s[38:39]
	s_cbranch_vccnz .Lg_402
	v_cvt_pk_bf16_f32 v36, v32, v33
	v_cvt_pk_bf16_f32 v37, v30, v31
	v_cvt_pk_bf16_f32 v38, v28, v29
	v_cvt_pk_bf16_f32 v39, v26, v27
	s_mov_b64 s[60:61], 0
	global_store_dwordx4 v[34:35], v[36:39], off nt
	s_nop 1
	v_cvt_pk_bf16_f32 v36, v24, v25
	v_cvt_pk_bf16_f32 v37, v22, v23
	v_cvt_pk_bf16_f32 v38, v20, v21
	v_cvt_pk_bf16_f32 v39, v18, v19
	global_store_dwordx4 v[34:35], v[36:39], off offset:256 nt
; __device__ __forceinline__ unsigned cvt_pk_bf16(float lo, float hi) { unsigned r; asm volatile("v_cvt_pk_bf16_f32 %0, %1, %2" : "=v"(r) : "v"(lo), "v"(hi)); return r; }
; __device__ __forceinline__ void stats_mr(const f32x2 s, float& mu, float& r) { mu = s.x * (1.0f / 1024.0f); const float var = s.y * (1.0f / 1024.0f) - mu * mu; r = __builtin_amdgcn_rsqf(var + 1e-5f); }
;     __device__ __forceinline__ void operator()(const f32x4 (&acc)[2][2][4][2], const Unit& u, int wr, int wc, int fr, int fq) const {
;     ...
;             for (int m = 0; m < 4; ++m) { const int row = row0 + ai * HALF + m * 16; bf16_t* rowp = O + (size_t)row * ldc + dst0 + lc;
;                 float mu, r; stats_mr(sv[ai][m], mu, r);
;                 const f32x4 a0 = (acc[ai][0][m][0] - cv[0][0] * mu) * r + bv[0][0], a1 = (acc[ai][0][m][1] - cv[0][1] * mu) * r + bv[0][1];
;                 const f32x4 b0 = (acc[ai][1][m][0] - cv[1][0] * mu) * r + bv[1][0], b1 = (acc[ai][1][m][1] - cv[1][1] * mu) * r + bv[1][1];
;                 if (pair) { const f32x4 p0 = a0 * b0, p1 = a1 * b1;
;                     u32x4 w; w.x = cvt_pk_bf16(p0[0], p0[1]); w.y = cvt_pk_bf16(p0[2], p0[3]); w.z = cvt_pk_bf16(p1[0], p1[1]); w.w = cvt_pk_bf16(p1[2], p1[3]);
;                     *(u32x4*)(rowp) = w; }
;                 else { u32x4 w; w.x = cvt_pk_bf16(a0[0], a0[1]); w.y = cvt_pk_bf16(a0[2], a0[3]); w.z = cvt_pk_bf16(a1[0], a1[1]); w.w = cvt_pk_bf16(a1[2], a1[3]);
;                     *(u32x4*)(rowp) = w;
;                     u32x4 x; x.x = cvt_pk_bf16(b0[0], b0[1]); x.y = cvt_pk_bf16(b0[2], b0[3]); x.z = cvt_pk_bf16(b1[0], b1[1]); x.w = cvt_pk_bf16(b1[2], b1[3]);
;                     *(u32x4*)(rowp + HALF) = x; } }
.Lg_402:
	s_andn2_b64 vcc, exec, s[60:61]
	s_cbranch_vccnz .Lg_404
	v_pk_mul_f32 v[20:21], v[28:29], v[20:21]
	v_pk_mul_f32 v[22:23], v[30:31], v[22:23]
	v_pk_mul_f32 v[24:25], v[32:33], v[24:25]
	v_pk_mul_f32 v[26:27], v[26:27], v[18:19]
	v_cvt_pk_bf16_f32 v18, v24, v25
	v_cvt_pk_bf16_f32 v19, v22, v23
	v_cvt_pk_bf16_f32 v20, v20, v21
	s_nop 0
	v_cvt_pk_bf16_f32 v21, v26, v27
	global_store_dwordx4 v[34:35], v[18:21], off nt
.Lg_404:
	s_nop 1
	v_pk_mul_f32 v[20:21], v[192:193], s[54:55] op_sel_hi:[1,0]
	v_mov_b64_e32 v[18:19], s[66:67]
	v_fma_f32 v22, -v20, v20, v21
	v_add_f32_e32 v22, 0x3727c5ac, v22
	v_rsq_f32_e32 v22, v22
	v_pk_fma_f32 v[16:17], v[50:51], v[20:21], v[16:17] op_sel_hi:[1,0,1]
	v_pk_fma_f32 v[24:25], v[154:155], v[20:21], v[14:15] op_sel_hi:[1,0,1] neg_lo:[1,0,0] neg_hi:[1,0,0]
	v_pk_fma_f32 v[12:13], v[20:21], v[136:137], v[12:13] op_sel_hi:[0,1,1] neg_lo:[1,0,0] neg_hi:[1,0,0]
	v_pk_fma_f32 v[14:15], v[16:17], v[22:23], v[152:153] op_sel_hi:[1,0,1]
	v_pk_fma_f32 v[16:17], v[24:25], v[22:23], v[150:151] op_sel_hi:[1,0,1]
	v_pk_fma_f32 v[24:25], v[20:21], v[134:135], v[10:11] op_sel_hi:[0,1,1] neg_lo:[1,0,0] neg_hi:[1,0,0]
	v_mad_i64_i32 v[18:19], s[60:61], v194, s55, v[18:19]
	v_pk_fma_f32 v[10:11], v[12:13], v[22:23], v[140:141] op_sel_hi:[1,0,1]
	v_pk_fma_f32 v[12:13], v[24:25], v[22:23], v[138:139] op_sel_hi:[1,0,1]
	v_xor_b32_e32 v25, 0x80000000, v149
	v_xor_b32_e32 v24, 0x80000000, v148
	v_lshl_add_u64 v[18:19], s[34:35], 1, v[18:19]
	v_mov_b32_e32 v197, v0
	v_pk_fma_f32 v[8:9], v[24:25], v[20:21], v[8:9] op_sel_hi:[1,0,1]
	v_pk_fma_f32 v[24:25], v[146:147], v[20:21], v[6:7] op_sel_hi:[1,0,1] neg_lo:[1,0,0] neg_hi:[1,0,0]
	v_pk_fma_f32 v[4:5], v[20:21], v[132:133], v[4:5] op_sel_hi:[0,1,1] neg_lo:[1,0,0] neg_hi:[1,0,0]
	v_pk_fma_f32 v[20:21], v[20:21], v[130:131], v[2:3] op_sel_hi:[0,1,1] neg_lo:[1,0,0] neg_hi:[1,0,0]
	v_lshl_add_u64 v[18:19], v[18:19], 0, v[196:197]
	v_pk_fma_f32 v[6:7], v[8:9], v[22:23], v[160:161] op_sel_hi:[1,0,1]
	v_pk_fma_f32 v[8:9], v[24:25], v[22:23], v[158:159] op_sel_hi:[1,0,1]
	v_pk_fma_f32 v[2:3], v[22:23], v[4:5], v[144:145] op_sel_hi:[0,1,1]
	v_pk_fma_f32 v[4:5], v[22:23], v[20:21], v[142:143] op_sel_hi:[0,1,1]
	s_mov_b64 s[34:35], -1
	s_and_b64 vcc, exec, s[38:39]
	s_cbranch_vccnz .Lg_406
	v_cvt_pk_bf16_f32 v20, v16, v17
	v_cvt_pk_bf16_f32 v21, v14, v15
	v_cvt_pk_bf16_f32 v22, v12, v13
	v_cvt_pk_bf16_f32 v23, v10, v11
	s_mov_b64 s[34:35], 0
	global_store_dwordx4 v[18:19], v[20:23], off nt
	s_nop 1
	v_cvt_pk_bf16_f32 v20, v8, v9
	v_cvt_pk_bf16_f32 v21, v6, v7
	v_cvt_pk_bf16_f32 v22, v4, v5
	v_cvt_pk_bf16_f32 v23, v2, v3
	global_store_dwordx4 v[18:19], v[20:23], off offset:256 nt
.Lg_406:
	s_andn2_b64 vcc, exec, s[34:35]
	s_cbranch_vccnz .LBB0_408
	v_pk_mul_f32 v[4:5], v[12:13], v[4:5]
	v_pk_mul_f32 v[6:7], v[14:15], v[6:7]
	v_pk_mul_f32 v[8:9], v[16:17], v[8:9]
	v_pk_mul_f32 v[10:11], v[10:11], v[2:3]
	v_cvt_pk_bf16_f32 v2, v8, v9
	v_cvt_pk_bf16_f32 v3, v6, v7
	v_cvt_pk_bf16_f32 v4, v4, v5
	s_nop 0
	v_cvt_pk_bf16_f32 v5, v10, v11
	global_store_dwordx4 v[18:19], v[2:5], off nt
	s_branch .LBB0_408
